# v16-plus-tight-polling
# baseline (speedup 1.0000x reference)
; __device__ __forceinline__ unsigned xb_ld(unsigned* p)              { return __hip_atomic_load(p, __ATOMIC_RELAXED, __HIP_MEMORY_SCOPE_AGENT); }
; __device__ __forceinline__ void xcd_barrier_complete(unsigned* bar, unsigned x, unsigned& nloc, unsigned& nx, unsigned expect) {
;     const unsigned G = expect ? expect : gridDim.x * gridDim.y * gridDim.z;
;     unsigned sum, cnt, mine, sp = 0u;
;     for (;;) {
;         sum = 0u; cnt = 0u; mine = 0u;
; #pragma unroll
;         for (unsigned j = 0; j < 16; ++j) { const unsigned c = xb_ld(&bar[XB_XCNT(j)]); sum += c; cnt += (c > 0u) ? 1u : 0u; mine = (j == x) ? c : mine; }
;         if (sum == G) break;
;         __builtin_amdgcn_s_sleep(1);
;         if ((++sp & 255u) == 0u) { if (xb_ld(&bar[XB_TMO])) break; if (sp > XB_SPIN_CAP) { atomicAdd(&bar[XB_TMO], 1u); break; } }
;     }
;     nloc = mine > 0u ? mine : 1u; nx = cnt > 0u ? cnt : 1u;
; }
.LBB0_96:
	global_load_dword v16, v17, s[6:7] sc1
	global_load_dword v1, v17, s[8:9] sc1
	global_load_dword v2, v17, s[28:29] sc1
	global_load_dword v3, v17, s[38:39] sc1
	global_load_dword v4, v17, s[40:41] sc1
	global_load_dword v5, v17, s[46:47] sc1
	global_load_dword v6, v17, s[50:51] sc1
	global_load_dword v7, v17, s[60:61] sc1
	global_load_dword v8, v17, s[62:63] sc1
	global_load_dword v9, v17, s[64:65] sc1
	global_load_dword v10, v17, s[66:67] sc1
	global_load_dword v11, v17, s[70:71] sc1
	global_load_dword v12, v17, s[74:75] sc1
	global_load_dword v13, v17, s[76:77] sc1
	global_load_dword v14, v17, s[78:79] sc1
	global_load_dword v15, v17, s[80:81] sc1
	s_mov_b64 s[82:83], -1
	s_mov_b64 s[84:85], -1
	s_waitcnt vmcnt(14)
	v_add_u32_e32 v18, v1, v16
	s_waitcnt vmcnt(13)
	v_add_u32_e32 v18, v18, v2
	s_waitcnt vmcnt(12)
	v_add_u32_e32 v18, v18, v3
	s_waitcnt vmcnt(11)
	v_add_u32_e32 v18, v18, v4
	s_waitcnt vmcnt(10)
	v_add_u32_e32 v18, v18, v5
	s_waitcnt vmcnt(9)
	v_add_u32_e32 v18, v18, v6
	s_waitcnt vmcnt(8)
	v_add_u32_e32 v18, v18, v7
	s_waitcnt vmcnt(7)
	v_add_u32_e32 v18, v18, v8
	s_waitcnt vmcnt(6)
	v_add_u32_e32 v18, v18, v9
	s_waitcnt vmcnt(5)
	v_add_u32_e32 v18, v18, v10
	s_waitcnt vmcnt(4)
	v_add_u32_e32 v18, v18, v11
	s_waitcnt vmcnt(3)
	v_add_u32_e32 v18, v18, v12
	s_waitcnt vmcnt(2)
	v_add_u32_e32 v18, v18, v13
	s_waitcnt vmcnt(1)
	v_add_u32_e32 v18, v18, v14
	s_waitcnt vmcnt(0)
	v_add_u32_e32 v18, v18, v15
	v_cmp_eq_u32_e32 vcc, s56, v18
	s_cbranch_vccnz .LBB0_95
	s_and_b32 s58, s57, 0xff
	s_cmp_eq_u32 s58, 0
	s_mov_b64 s[88:89], -1
	s_sleep 0
	s_cbranch_scc1 .LBB0_100
	s_and_b64 vcc, exec, s[88:89]
	s_cbranch_vccz .LBB0_95

; __device__ __forceinline__ unsigned xb_ld(unsigned* p)              { return __hip_atomic_load(p, __ATOMIC_RELAXED, __HIP_MEMORY_SCOPE_AGENT); }
; __device__ __forceinline__ unsigned xb_add(unsigned* p, unsigned v) { return __hip_atomic_fetch_add(p, v, __ATOMIC_RELAXED, __HIP_MEMORY_SCOPE_AGENT); }
; #define XB_SPIN(cond, bar) do { unsigned _sp = 0; while (cond) { __builtin_amdgcn_s_sleep(1); \
;     if ((++_sp & 255u) == 0u) { if (xb_ld(&(bar)[XB_TMO])) break; if (_sp > XB_SPIN_CAP) { atomicAdd(&(bar)[XB_TMO], 1u); break; } } } } while (0)
; __device__ __forceinline__ void xcd_barrier(const XcdBarrier& b, bool release = true) {
;     ...
;             if (og + 1u != tgt) XB_SPIN(xb_ld(&bar[XB_TOP]) < tgt, bar);
;             __builtin_amdgcn_fence(__ATOMIC_ACQUIRE, "agent");
;             xb_add(&bar[XB_XGEN(b.x)], 1u);
;             asm volatile("s_waitcnt vmcnt(0)" ::: "memory");
;         } else {
;             __builtin_amdgcn_fence(__ATOMIC_ACQUIRE, "agent");
;             XB_SPIN(xb_ld(&bar[XB_XGEN(b.x)]) == gen, bar);
.LBB0_113:
	s_and_b32 s57, s56, 0xff
	s_mov_b64 s[50:51], -1
	s_cmp_lg_u32 s57, 0
	s_mov_b64 s[62:63], -1
	s_sleep 0
	s_cbranch_scc0 .LBB0_116
	s_and_b64 vcc, exec, s[62:63]
	s_cbranch_vccz .LBB0_112

; __device__ __forceinline__ unsigned xb_ld(unsigned* p)              { return __hip_atomic_load(p, __ATOMIC_RELAXED, __HIP_MEMORY_SCOPE_AGENT); }
; __device__ __forceinline__ unsigned xb_add(unsigned* p, unsigned v) { return __hip_atomic_fetch_add(p, v, __ATOMIC_RELAXED, __HIP_MEMORY_SCOPE_AGENT); }
; #define XB_SPIN(cond, bar) do { unsigned _sp = 0; while (cond) { __builtin_amdgcn_s_sleep(1); \
;     if ((++_sp & 255u) == 0u) { if (xb_ld(&(bar)[XB_TMO])) break; if (_sp > XB_SPIN_CAP) { atomicAdd(&(bar)[XB_TMO], 1u); break; } } } } while (0)
; __device__ __forceinline__ void xcd_barrier(const XcdBarrier& b, bool release = true) {
;     ...
;             if (og + 1u != tgt) XB_SPIN(xb_ld(&bar[XB_TOP]) < tgt, bar);
;             __builtin_amdgcn_fence(__ATOMIC_ACQUIRE, "agent");
;             xb_add(&bar[XB_XGEN(b.x)], 1u);
;             asm volatile("s_waitcnt vmcnt(0)" ::: "memory");
;         } else {
;             __builtin_amdgcn_fence(__ATOMIC_ACQUIRE, "agent");
;             XB_SPIN(xb_ld(&bar[XB_XGEN(b.x)]) == gen, bar);
.LBB0_130:
	s_and_b32 s50, s56, 0xff
	s_mov_b64 s[46:47], -1
	s_cmp_lg_u32 s50, 0
	s_mov_b64 s[60:61], -1
	s_sleep 0
	s_cbranch_scc0 .LBB0_133
	s_and_b64 vcc, exec, s[60:61]
	s_cbranch_vccz .LBB0_129

; __global__ void __launch_bounds__(NWAVES * 64, 2) mk_fwd(Args args) {
;     ...
;             if (wave == 0) { const unsigned long long t0 = __builtin_amdgcn_s_memrealtime(); const int p0 = (bx - 128) >> 4;
;                 for (;;) { unsigned mn = 4u;
; #pragma unroll
;                     for (int k = 0; k < 4; ++k) { const unsigned v = __hip_atomic_load((unsigned*)(ws + WS_CTL) + CW_PCNT + 64 * (p0 + 8 * k), __ATOMIC_RELAXED, __HIP_MEMORY_SCOPE_AGENT); mn = v < mn ? v : mn; }
;                     if ((unsigned)__builtin_amdgcn_readfirstlane(mn) >= 4u) break;
;                     if (__builtin_amdgcn_s_memrealtime() - t0 > 2000000ull) { if (lane == 0) __hip_atomic_store((unsigned*)(ws + WS_CTL), 1u, __ATOMIC_RELAXED, __HIP_MEMORY_SCOPE_AGENT); break; }
;                     __builtin_amdgcn_s_sleep(2); } }
.LBB0_393:
	global_load_dword v4, v1, s[2:3] sc1
	global_load_dword v5, v1, s[4:5] sc1
	global_load_dword v6, v1, s[6:7] sc1
	global_load_dword v7, v1, s[8:9] sc1
	s_mov_b64 s[18:19], -1
	s_waitcnt vmcnt(1)
	v_min3_u32 v4, v4, v5, v6
	s_waitcnt vmcnt(0)
	v_min3_u32 v4, v4, v7, 4
	s_nop 0
	v_readfirstlane_b32 s20, v4
	s_cmp_gt_u32 s20, 3
	s_mov_b64 s[20:21], -1
	s_cbranch_scc1 .LBB0_392
	s_memrealtime s[18:19]
	s_waitcnt lgkmcnt(0)
	s_sub_u32 s18, s18, s0
	s_subb_u32 s19, s19, s1
	v_cmp_lt_u64_e32 vcc, s[18:19], v[2:3]
	s_cbranch_vccz .LBB0_391
	s_mov_b64 s[20:21], 0
	s_sleep 0
	s_branch .LBB0_391

; __global__ void __launch_bounds__(NWAVES * 64, 2) mk_fwd(Args args) {
;     ...
;             if (wave == 0) { const unsigned long long t0 = __builtin_amdgcn_s_memrealtime();
;                 while ((unsigned)__builtin_amdgcn_readfirstlane(__hip_atomic_load((unsigned*)(ws + WS_CTL) + CW_S5DONE, __ATOMIC_RELAXED, __HIP_MEMORY_SCOPE_AGENT)) < 128u) {
;                     if (__builtin_amdgcn_s_memrealtime() - t0 > 2000000ull) { if (lane == 0) __hip_atomic_store((unsigned*)(ws + WS_CTL), 1u, __ATOMIC_RELAXED, __HIP_MEMORY_SCOPE_AGENT); break; }
;                     __builtin_amdgcn_s_sleep(2); } }
.LBB0_402:
	global_load_dword v4, v1, s[2:3] sc1
	s_mov_b64 s[4:5], -1
	s_waitcnt vmcnt(0)
	v_readfirstlane_b32 s6, v4
	s_cmpk_gt_u32 s6, 0x7f
	s_mov_b64 s[6:7], -1
	s_cbranch_scc1 .LBB0_401
	s_memrealtime s[4:5]
	s_waitcnt lgkmcnt(0)
	s_sub_u32 s4, s4, s0
	s_subb_u32 s5, s5, s1
	v_cmp_lt_u64_e32 vcc, s[4:5], v[2:3]
	s_cbranch_vccz .LBB0_400
	s_mov_b64 s[6:7], 0
	s_sleep 0
	s_branch .LBB0_400

; __global__ void __launch_bounds__(NWAVES * 64, 2) mk_fwd(Args args) {
;     ...
;                 if (half == 1 && wave == 0) {
;                     const unsigned long long t0 = __builtin_amdgcn_s_memrealtime();
;                     while ((unsigned)__builtin_amdgcn_readfirstlane(__hip_atomic_load(CFLAG, __ATOMIC_RELAXED, __HIP_MEMORY_SCOPE_AGENT)) == 0u) {
;                         if (__builtin_amdgcn_s_memrealtime() - t0 > 2000000ull) { if (lane == 0) __hip_atomic_store((unsigned*)(ws + WS_CTL), 1u, __ATOMIC_RELAXED, __HIP_MEMORY_SCOPE_AGENT); break; }
;                         __builtin_amdgcn_s_sleep(2); }
;                 }
.LBB0_446:
	global_load_dword v66, v197, s[38:39] sc1
	s_mov_b64 s[72:73], -1
	s_mov_b64 s[74:75], -1
	s_waitcnt vmcnt(0)
	v_readfirstlane_b32 s35, v66
	s_cmp_lg_u32 s35, 0
	s_cbranch_scc1 .LBB0_445
	s_memrealtime s[58:59]
	s_waitcnt lgkmcnt(0)
	s_sub_u32 s58, s58, s70
	s_subb_u32 s59, s59, s71
	v_cmp_lt_u64_e32 vcc, s[58:59], v[208:209]
	s_cbranch_vccz .LBB0_444
	s_mov_b64 s[74:75], 0
	s_sleep 0
	s_branch .LBB0_444

; __device__ __forceinline__ unsigned xb_ld(unsigned* p)              { return __hip_atomic_load(p, __ATOMIC_RELAXED, __HIP_MEMORY_SCOPE_AGENT); }
; __device__ __forceinline__ void xcd_barrier_complete(unsigned* bar, unsigned x, unsigned& nloc, unsigned& nx, unsigned expect) {
;     const unsigned G = expect ? expect : gridDim.x * gridDim.y * gridDim.z;
;     unsigned sum, cnt, mine, sp = 0u;
;     for (;;) {
;         sum = 0u; cnt = 0u; mine = 0u;
; #pragma unroll
;         for (unsigned j = 0; j < 16; ++j) { const unsigned c = xb_ld(&bar[XB_XCNT(j)]); sum += c; cnt += (c > 0u) ? 1u : 0u; mine = (j == x) ? c : mine; }
;         if (sum == G) break;
;         __builtin_amdgcn_s_sleep(1);
;         if ((++sp & 255u) == 0u) { if (xb_ld(&bar[XB_TMO])) break; if (sp > XB_SPIN_CAP) { atomicAdd(&bar[XB_TMO], 1u); break; } }
;     }
;     nloc = mine > 0u ? mine : 1u; nx = cnt > 0u ? cnt : 1u;
; }
.LBB0_554:
	global_load_dword v16, v17, s[12:13] sc1
	global_load_dword v1, v17, s[14:15] sc1
	global_load_dword v2, v17, s[16:17] sc1
	global_load_dword v3, v17, s[20:21] sc1
	global_load_dword v4, v17, s[22:23] sc1
	global_load_dword v5, v17, s[30:31] sc1
	global_load_dword v6, v17, s[34:35] sc1
	global_load_dword v7, v17, s[38:39] sc1
	global_load_dword v8, v17, s[42:43] sc1
	global_load_dword v9, v17, s[44:45] sc1
	global_load_dword v10, v17, s[46:47] sc1
	global_load_dword v11, v17, s[48:49] sc1
	global_load_dword v12, v17, s[50:51] sc1
	global_load_dword v13, v17, s[62:63] sc1
	global_load_dword v14, v17, s[66:67] sc1
	global_load_dword v15, v17, s[68:69] sc1
	s_mov_b64 s[70:71], -1
	s_mov_b64 s[72:73], -1
	s_waitcnt vmcnt(14)
	v_add_u32_e32 v18, v1, v16
	s_waitcnt vmcnt(13)
	v_add_u32_e32 v18, v18, v2
	s_waitcnt vmcnt(12)
	v_add_u32_e32 v18, v18, v3
	s_waitcnt vmcnt(11)
	v_add_u32_e32 v18, v18, v4
	s_waitcnt vmcnt(10)
	v_add_u32_e32 v18, v18, v5
	s_waitcnt vmcnt(9)
	v_add_u32_e32 v18, v18, v6
	s_waitcnt vmcnt(8)
	v_add_u32_e32 v18, v18, v7
	s_waitcnt vmcnt(7)
	v_add_u32_e32 v18, v18, v8
	s_waitcnt vmcnt(6)
	v_add_u32_e32 v18, v18, v9
	s_waitcnt vmcnt(5)
	v_add_u32_e32 v18, v18, v10
	s_waitcnt vmcnt(4)
	v_add_u32_e32 v18, v18, v11
	s_waitcnt vmcnt(3)
	v_add_u32_e32 v18, v18, v12
	s_waitcnt vmcnt(2)
	v_add_u32_e32 v18, v18, v13
	s_waitcnt vmcnt(1)
	v_add_u32_e32 v18, v18, v14
	s_waitcnt vmcnt(0)
	v_add_u32_e32 v18, v18, v15
	v_cmp_eq_u32_e32 vcc, s5, v18
	s_cbranch_vccnz .LBB0_553
	s_and_b32 s41, s10, 0xff
	s_cmp_eq_u32 s41, 0
	s_mov_b64 s[74:75], -1
	s_sleep 0
	s_cbranch_scc1 .LBB0_558
	s_and_b64 vcc, exec, s[74:75]
	s_cbranch_vccz .LBB0_553

; __device__ __forceinline__ unsigned xb_ld(unsigned* p)              { return __hip_atomic_load(p, __ATOMIC_RELAXED, __HIP_MEMORY_SCOPE_AGENT); }
; __device__ __forceinline__ unsigned xb_add(unsigned* p, unsigned v) { return __hip_atomic_fetch_add(p, v, __ATOMIC_RELAXED, __HIP_MEMORY_SCOPE_AGENT); }
; #define XB_SPIN(cond, bar) do { unsigned _sp = 0; while (cond) { __builtin_amdgcn_s_sleep(1); \
;     if ((++_sp & 255u) == 0u) { if (xb_ld(&(bar)[XB_TMO])) break; if (_sp > XB_SPIN_CAP) { atomicAdd(&(bar)[XB_TMO], 1u); break; } } } } while (0)
; __device__ __forceinline__ void xcd_barrier(const XcdBarrier& b, bool release = true) {
;     ...
;             if (og + 1u != tgt) XB_SPIN(xb_ld(&bar[XB_TOP]) < tgt, bar);
;             __builtin_amdgcn_fence(__ATOMIC_ACQUIRE, "agent");
;             xb_add(&bar[XB_XGEN(b.x)], 1u);
;             asm volatile("s_waitcnt vmcnt(0)" ::: "memory");
;         } else {
;             __builtin_amdgcn_fence(__ATOMIC_ACQUIRE, "agent");
;             XB_SPIN(xb_ld(&bar[XB_XGEN(b.x)]) == gen, bar);
.LBB0_570:
	s_and_b32 s10, s5, 0xff
	s_mov_b64 s[34:35], -1
	s_cmp_lg_u32 s10, 0
	s_mov_b64 s[42:43], -1
	s_sleep 0
	s_cbranch_scc0 .LBB0_573
	s_and_b64 vcc, exec, s[42:43]
	s_cbranch_vccz .LBB0_569

; __device__ __forceinline__ unsigned xb_ld(unsigned* p)              { return __hip_atomic_load(p, __ATOMIC_RELAXED, __HIP_MEMORY_SCOPE_AGENT); }
; __device__ __forceinline__ unsigned xb_add(unsigned* p, unsigned v) { return __hip_atomic_fetch_add(p, v, __ATOMIC_RELAXED, __HIP_MEMORY_SCOPE_AGENT); }
; #define XB_SPIN(cond, bar) do { unsigned _sp = 0; while (cond) { __builtin_amdgcn_s_sleep(1); \
;     if ((++_sp & 255u) == 0u) { if (xb_ld(&(bar)[XB_TMO])) break; if (_sp > XB_SPIN_CAP) { atomicAdd(&(bar)[XB_TMO], 1u); break; } } } } while (0)
; __device__ __forceinline__ void xcd_barrier(const XcdBarrier& b, bool release = true) {
;     ...
;             if (og + 1u != tgt) XB_SPIN(xb_ld(&bar[XB_TOP]) < tgt, bar);
;             __builtin_amdgcn_fence(__ATOMIC_ACQUIRE, "agent");
;             xb_add(&bar[XB_XGEN(b.x)], 1u);
;             asm volatile("s_waitcnt vmcnt(0)" ::: "memory");
;         } else {
;             __builtin_amdgcn_fence(__ATOMIC_ACQUIRE, "agent");
;             XB_SPIN(xb_ld(&bar[XB_XGEN(b.x)]) == gen, bar);
.LBB0_592:
	s_and_b32 s10, s5, 0xff
	s_mov_b64 s[30:31], -1
	s_cmp_lg_u32 s10, 0
	s_mov_b64 s[38:39], -1
	s_sleep 0
	s_cbranch_scc0 .LBB0_595
	s_and_b64 vcc, exec, s[38:39]
	s_cbranch_vccz .LBB0_591

;     __device__ __forceinline__ void run(const Unit& u, PG8_LAS unsigned char* lds, int wid, int lane) const {
;     ...
;         if (wid == 0) {
;             const unsigned long long t0 = __builtin_amdgcn_s_memrealtime();
;             for (;;) {
;                 if ((unsigned)__builtin_amdgcn_readfirstlane(__hip_atomic_load(cnt + 64 * u.pm, __ATOMIC_RELAXED, __HIP_MEMORY_SCOPE_AGENT)) >= 32u) break;
;                 if (__builtin_amdgcn_s_memrealtime() - t0 > 2000000ull) { if (lane == 0) __hip_atomic_store(tmo, 1u, __ATOMIC_RELAXED, __HIP_MEMORY_SCOPE_AGENT); break; }
;                 __builtin_amdgcn_s_sleep(2);
;             }
.LBB0_709:
	global_load_dword v142, v141, s[6:7] sc1
	s_mov_b64 s[14:15], -1
	s_mov_b64 s[16:17], -1
	s_waitcnt vmcnt(0)
	v_readfirstlane_b32 s3, v142
	s_cmp_gt_u32 s3, 31
	s_cbranch_scc1 .LBB0_708
	s_memrealtime s[14:15]
	s_waitcnt lgkmcnt(0)
	s_sub_u32 s14, s14, s4
	s_subb_u32 s15, s15, s5
	v_cmp_lt_u64_e32 vcc, s[14:15], v[138:139]
	s_cbranch_vccz .LBB0_707
	s_mov_b64 s[16:17], 0
	s_sleep 0
	s_branch .LBB0_707

; __device__ __forceinline__ unsigned xb_ld(unsigned* p)              { return __hip_atomic_load(p, __ATOMIC_RELAXED, __HIP_MEMORY_SCOPE_AGENT); }
; __device__ __forceinline__ void xcd_barrier_complete(unsigned* bar, unsigned x, unsigned& nloc, unsigned& nx, unsigned expect) {
;     const unsigned G = expect ? expect : gridDim.x * gridDim.y * gridDim.z;
;     unsigned sum, cnt, mine, sp = 0u;
;     for (;;) {
;         sum = 0u; cnt = 0u; mine = 0u;
; #pragma unroll
;         for (unsigned j = 0; j < 16; ++j) { const unsigned c = xb_ld(&bar[XB_XCNT(j)]); sum += c; cnt += (c > 0u) ? 1u : 0u; mine = (j == x) ? c : mine; }
;         if (sum == G) break;
;         __builtin_amdgcn_s_sleep(1);
;         if ((++sp & 255u) == 0u) { if (xb_ld(&bar[XB_TMO])) break; if (sp > XB_SPIN_CAP) { atomicAdd(&bar[XB_TMO], 1u); break; } }
;     }
;     nloc = mine > 0u ? mine : 1u; nx = cnt > 0u ? cnt : 1u;
; }
.LBB0_730:
	global_load_dword v16, v17, s[6:7] sc1
	global_load_dword v1, v17, s[12:13] sc1
	global_load_dword v2, v17, s[14:15] sc1
	global_load_dword v3, v17, s[16:17] sc1
	global_load_dword v4, v17, s[18:19] sc1
	global_load_dword v5, v17, s[20:21] sc1
	global_load_dword v6, v17, s[22:23] sc1
	global_load_dword v7, v17, s[30:31] sc1
	global_load_dword v8, v17, s[34:35] sc1
	global_load_dword v9, v17, s[36:37] sc1
	global_load_dword v10, v17, s[38:39] sc1
	global_load_dword v11, v17, s[42:43] sc1
	global_load_dword v12, v17, s[44:45] sc1
	global_load_dword v13, v17, s[46:47] sc1
	global_load_dword v14, v17, s[48:49] sc1
	global_load_dword v15, v17, s[50:51] sc1
	s_mov_b64 s[62:63], -1
	s_mov_b64 s[64:65], -1
	s_waitcnt vmcnt(14)
	v_add_u32_e32 v18, v1, v16
	s_waitcnt vmcnt(13)
	v_add_u32_e32 v18, v18, v2
	s_waitcnt vmcnt(12)
	v_add_u32_e32 v18, v18, v3
	s_waitcnt vmcnt(11)
	v_add_u32_e32 v18, v18, v4
	s_waitcnt vmcnt(10)
	v_add_u32_e32 v18, v18, v5
	s_waitcnt vmcnt(9)
	v_add_u32_e32 v18, v18, v6
	s_waitcnt vmcnt(8)
	v_add_u32_e32 v18, v18, v7
	s_waitcnt vmcnt(7)
	v_add_u32_e32 v18, v18, v8
	s_waitcnt vmcnt(6)
	v_add_u32_e32 v18, v18, v9
	s_waitcnt vmcnt(5)
	v_add_u32_e32 v18, v18, v10
	s_waitcnt vmcnt(4)
	v_add_u32_e32 v18, v18, v11
	s_waitcnt vmcnt(3)
	v_add_u32_e32 v18, v18, v12
	s_waitcnt vmcnt(2)
	v_add_u32_e32 v18, v18, v13
	s_waitcnt vmcnt(1)
	v_add_u32_e32 v18, v18, v14
	s_waitcnt vmcnt(0)
	v_add_u32_e32 v18, v18, v15
	v_cmp_eq_u32_e32 vcc, s10, v18
	s_cbranch_vccnz .LBB0_729
	s_and_b32 s56, s41, 0xff
	s_cmp_eq_u32 s56, 0
	s_mov_b64 s[66:67], -1
	s_sleep 0
	s_cbranch_scc1 .LBB0_734
	s_and_b64 vcc, exec, s[66:67]
	s_cbranch_vccz .LBB0_729

; __device__ __forceinline__ unsigned xb_ld(unsigned* p)              { return __hip_atomic_load(p, __ATOMIC_RELAXED, __HIP_MEMORY_SCOPE_AGENT); }
; __device__ __forceinline__ unsigned xb_add(unsigned* p, unsigned v) { return __hip_atomic_fetch_add(p, v, __ATOMIC_RELAXED, __HIP_MEMORY_SCOPE_AGENT); }
; #define XB_SPIN(cond, bar) do { unsigned _sp = 0; while (cond) { __builtin_amdgcn_s_sleep(1); \
;     if ((++_sp & 255u) == 0u) { if (xb_ld(&(bar)[XB_TMO])) break; if (_sp > XB_SPIN_CAP) { atomicAdd(&(bar)[XB_TMO], 1u); break; } } } } while (0)
; __device__ __forceinline__ void xcd_barrier(const XcdBarrier& b, bool release = true) {
;     ...
;             if (og + 1u != tgt) XB_SPIN(xb_ld(&bar[XB_TOP]) < tgt, bar);
;             __builtin_amdgcn_fence(__ATOMIC_ACQUIRE, "agent");
;             xb_add(&bar[XB_XGEN(b.x)], 1u);
;             asm volatile("s_waitcnt vmcnt(0)" ::: "memory");
;         } else {
;             __builtin_amdgcn_fence(__ATOMIC_ACQUIRE, "agent");
;             XB_SPIN(xb_ld(&bar[XB_XGEN(b.x)]) == gen, bar);
.LBB0_746:
	s_and_b32 s30, s10, 0xff
	s_mov_b64 s[22:23], -1
	s_cmp_lg_u32 s30, 0
	s_mov_b64 s[34:35], -1
	s_sleep 0
	s_cbranch_scc0 .LBB0_749
	s_and_b64 vcc, exec, s[34:35]
	s_cbranch_vccz .LBB0_745

; __device__ __forceinline__ unsigned xb_ld(unsigned* p)              { return __hip_atomic_load(p, __ATOMIC_RELAXED, __HIP_MEMORY_SCOPE_AGENT); }
; __device__ __forceinline__ unsigned xb_add(unsigned* p, unsigned v) { return __hip_atomic_fetch_add(p, v, __ATOMIC_RELAXED, __HIP_MEMORY_SCOPE_AGENT); }
; #define XB_SPIN(cond, bar) do { unsigned _sp = 0; while (cond) { __builtin_amdgcn_s_sleep(1); \
;     if ((++_sp & 255u) == 0u) { if (xb_ld(&(bar)[XB_TMO])) break; if (_sp > XB_SPIN_CAP) { atomicAdd(&(bar)[XB_TMO], 1u); break; } } } } while (0)
; __device__ __forceinline__ void xcd_barrier(const XcdBarrier& b, bool release = true) {
;     ...
;             if (og + 1u != tgt) XB_SPIN(xb_ld(&bar[XB_TOP]) < tgt, bar);
;             __builtin_amdgcn_fence(__ATOMIC_ACQUIRE, "agent");
;             xb_add(&bar[XB_XGEN(b.x)], 1u);
;             asm volatile("s_waitcnt vmcnt(0)" ::: "memory");
;         } else {
;             __builtin_amdgcn_fence(__ATOMIC_ACQUIRE, "agent");
;             XB_SPIN(xb_ld(&bar[XB_XGEN(b.x)]) == gen, bar);
.LBB0_765:
	s_and_b32 s22, s10, 0xff
	s_mov_b64 s[20:21], -1
	s_cmp_lg_u32 s22, 0
	s_mov_b64 s[30:31], -1
	s_sleep 0
	s_cbranch_scc0 .LBB0_768
	s_and_b64 vcc, exec, s[30:31]
	s_cbranch_vccz .LBB0_764

; __device__ __forceinline__ unsigned xb_ld(unsigned* p)              { return __hip_atomic_load(p, __ATOMIC_RELAXED, __HIP_MEMORY_SCOPE_AGENT); }
; __device__ __forceinline__ void xcd_barrier_complete(unsigned* bar, unsigned x, unsigned& nloc, unsigned& nx, unsigned expect) {
;     const unsigned G = expect ? expect : gridDim.x * gridDim.y * gridDim.z;
;     unsigned sum, cnt, mine, sp = 0u;
;     for (;;) {
;         sum = 0u; cnt = 0u; mine = 0u;
; #pragma unroll
;         for (unsigned j = 0; j < 16; ++j) { const unsigned c = xb_ld(&bar[XB_XCNT(j)]); sum += c; cnt += (c > 0u) ? 1u : 0u; mine = (j == x) ? c : mine; }
;         if (sum == G) break;
;         __builtin_amdgcn_s_sleep(1);
;         if ((++sp & 255u) == 0u) { if (xb_ld(&bar[XB_TMO])) break; if (sp > XB_SPIN_CAP) { atomicAdd(&bar[XB_TMO], 1u); break; } }
;     }
;     nloc = mine > 0u ? mine : 1u; nx = cnt > 0u ? cnt : 1u;
; }
.LBB0_825:
	global_load_dword v16, v17, s[6:7] sc1
	global_load_dword v1, v17, s[8:9] sc1
	global_load_dword v2, v17, s[14:15] sc1
	global_load_dword v3, v17, s[16:17] sc1
	global_load_dword v4, v17, s[18:19] sc1
	global_load_dword v5, v17, s[20:21] sc1
	global_load_dword v6, v17, s[22:23] sc1
	global_load_dword v7, v17, s[24:25] sc1
	global_load_dword v8, v17, s[30:31] sc1
	global_load_dword v9, v17, s[34:35] sc1
	global_load_dword v10, v17, s[36:37] sc1
	global_load_dword v11, v17, s[38:39] sc1
	global_load_dword v12, v17, s[40:41] sc1
	global_load_dword v13, v17, s[42:43] sc1
	global_load_dword v14, v17, s[44:45] sc1
	global_load_dword v15, v17, s[46:47] sc1
	s_mov_b64 s[48:49], -1
	s_mov_b64 s[50:51], -1
	s_waitcnt vmcnt(14)
	v_add_u32_e32 v18, v1, v16
	s_waitcnt vmcnt(13)
	v_add_u32_e32 v18, v18, v2
	s_waitcnt vmcnt(12)
	v_add_u32_e32 v18, v18, v3
	s_waitcnt vmcnt(11)
	v_add_u32_e32 v18, v18, v4
	s_waitcnt vmcnt(10)
	v_add_u32_e32 v18, v18, v5
	s_waitcnt vmcnt(9)
	v_add_u32_e32 v18, v18, v6
	s_waitcnt vmcnt(8)
	v_add_u32_e32 v18, v18, v7
	s_waitcnt vmcnt(7)
	v_add_u32_e32 v18, v18, v8
	s_waitcnt vmcnt(6)
	v_add_u32_e32 v18, v18, v9
	s_waitcnt vmcnt(5)
	v_add_u32_e32 v18, v18, v10
	s_waitcnt vmcnt(4)
	v_add_u32_e32 v18, v18, v11
	s_waitcnt vmcnt(3)
	v_add_u32_e32 v18, v18, v12
	s_waitcnt vmcnt(2)
	v_add_u32_e32 v18, v18, v13
	s_waitcnt vmcnt(1)
	v_add_u32_e32 v18, v18, v14
	s_waitcnt vmcnt(0)
	v_add_u32_e32 v18, v18, v15
	v_cmp_eq_u32_e32 vcc, s13, v18
	s_cbranch_vccnz .LBB0_824
	s_and_b32 s48, s29, 0xff
	s_cmp_eq_u32 s48, 0
	s_mov_b64 s[48:49], -1
	s_mov_b64 s[60:61], -1
	s_sleep 0
	s_cbranch_scc1 .LBB0_829
	s_and_b64 vcc, exec, s[60:61]
	s_cbranch_vccz .LBB0_824

; __device__ __forceinline__ unsigned xb_ld(unsigned* p)              { return __hip_atomic_load(p, __ATOMIC_RELAXED, __HIP_MEMORY_SCOPE_AGENT); }
; __device__ __forceinline__ unsigned xb_add(unsigned* p, unsigned v) { return __hip_atomic_fetch_add(p, v, __ATOMIC_RELAXED, __HIP_MEMORY_SCOPE_AGENT); }
; #define XB_SPIN(cond, bar) do { unsigned _sp = 0; while (cond) { __builtin_amdgcn_s_sleep(1); \
;     if ((++_sp & 255u) == 0u) { if (xb_ld(&(bar)[XB_TMO])) break; if (_sp > XB_SPIN_CAP) { atomicAdd(&(bar)[XB_TMO], 1u); break; } } } } while (0)
; __device__ __forceinline__ void xcd_barrier(const XcdBarrier& b, bool release = true) {
;     ...
;             if (og + 1u != tgt) XB_SPIN(xb_ld(&bar[XB_TOP]) < tgt, bar);
;             __builtin_amdgcn_fence(__ATOMIC_ACQUIRE, "agent");
;             xb_add(&bar[XB_XGEN(b.x)], 1u);
;             asm volatile("s_waitcnt vmcnt(0)" ::: "memory");
;         } else {
;             __builtin_amdgcn_fence(__ATOMIC_ACQUIRE, "agent");
;             XB_SPIN(xb_ld(&bar[XB_XGEN(b.x)]) == gen, bar);
.LBB0_841:
	s_and_b32 s24, s13, 0xff
	s_mov_b64 s[22:23], -1
	s_cmp_lg_u32 s24, 0
	s_mov_b64 s[30:31], -1
	s_sleep 0
	s_cbranch_scc0 .LBB0_844
	s_and_b64 vcc, exec, s[30:31]
	s_cbranch_vccz .LBB0_840

; __device__ __forceinline__ unsigned xb_ld(unsigned* p)              { return __hip_atomic_load(p, __ATOMIC_RELAXED, __HIP_MEMORY_SCOPE_AGENT); }
; __device__ __forceinline__ unsigned xb_add(unsigned* p, unsigned v) { return __hip_atomic_fetch_add(p, v, __ATOMIC_RELAXED, __HIP_MEMORY_SCOPE_AGENT); }
; #define XB_SPIN(cond, bar) do { unsigned _sp = 0; while (cond) { __builtin_amdgcn_s_sleep(1); \
;     if ((++_sp & 255u) == 0u) { if (xb_ld(&(bar)[XB_TMO])) break; if (_sp > XB_SPIN_CAP) { atomicAdd(&(bar)[XB_TMO], 1u); break; } } } } while (0)
; __device__ __forceinline__ void xcd_barrier(const XcdBarrier& b, bool release = true) {
;     ...
;             if (og + 1u != tgt) XB_SPIN(xb_ld(&bar[XB_TOP]) < tgt, bar);
;             __builtin_amdgcn_fence(__ATOMIC_ACQUIRE, "agent");
;             xb_add(&bar[XB_XGEN(b.x)], 1u);
;             asm volatile("s_waitcnt vmcnt(0)" ::: "memory");
;         } else {
;             __builtin_amdgcn_fence(__ATOMIC_ACQUIRE, "agent");
;             XB_SPIN(xb_ld(&bar[XB_XGEN(b.x)]) == gen, bar);
.LBB0_858:
	s_and_b32 s22, s13, 0xff
	s_mov_b64 s[20:21], -1
	s_cmp_lg_u32 s22, 0
	s_mov_b64 s[24:25], -1
	s_sleep 0
	s_cbranch_scc0 .LBB0_861
	s_and_b64 vcc, exec, s[24:25]
	s_cbranch_vccz .LBB0_857

;     __device__ __forceinline__ void run(const Unit& u, PG8_LAS unsigned char* lds, int wid, int lane) const {
;     ...
;         if (wid == 0) {
;             const unsigned long long t0 = __builtin_amdgcn_s_memrealtime();
;             for (;;) {
;                 if ((unsigned)__builtin_amdgcn_readfirstlane(__hip_atomic_load(cnt + 64 * u.pm, __ATOMIC_RELAXED, __HIP_MEMORY_SCOPE_AGENT)) >= 32u) break;
;                 if (__builtin_amdgcn_s_memrealtime() - t0 > 2000000ull) { if (lane == 0) __hip_atomic_store(tmo, 1u, __ATOMIC_RELAXED, __HIP_MEMORY_SCOPE_AGENT); break; }
;                 __builtin_amdgcn_s_sleep(2);
;             }
.LBB0_971:
	global_load_dword v8, v7, s[4:5] sc1
	s_mov_b64 s[10:11], -1
	s_waitcnt vmcnt(0)
	v_readfirstlane_b32 s12, v8
	s_cmp_gt_u32 s12, 31
	s_mov_b64 s[12:13], -1
	s_cbranch_scc1 .LBB0_970
	s_memrealtime s[10:11]
	s_waitcnt lgkmcnt(0)
	s_sub_u32 s10, s10, s0
	s_subb_u32 s11, s11, s1
	v_cmp_lt_u64_e32 vcc, s[10:11], v[4:5]
	s_cbranch_vccz .LBB0_969
	s_mov_b64 s[12:13], 0
	s_sleep 0
	s_branch .LBB0_969
